# gMLP staging norm: rstd via v_rsq_f32 instead of the serial IEEE sqrt+div chain (instruction selection, lever 7)
# baseline (speedup 1.0000x reference)
; __device__ __forceinline__ void gmlp_phase(const Params& p, LAS unsigned char* lds, int G) {
;     ...
;             const int i = 32 * wi + l32; const size_t tok = (size_t)(row0 + i);
;             const int cb = g * 128 + 64 * wc + 4 * hi;
;             const bf16_t* ap = WSM + (size_t)(g * 128 + i) * 128 + 8 * hi;
;             bf16x8 wf[8]; u32x2 guv[8];
; #pragma unroll
;             for (int ks = 0; ks < 8; ++ks) wf[ks] = *(const bf16x8*)(ap + 16 * ks);
; #pragma unroll
;             for (int q = 0; q < 4; ++q) { guv[2 * q] = *(const u32x2*)(GU + tok * 512 + cb + 8 * q); guv[2 * q + 1] = *(const u32x2*)(GU + tok * 512 + cb + 32 + 8 * q); }
;             const float bi = bs[g * 128 + i];
;             {
;                 float f[32];
;                 f[0] = bflo(v0.x); f[1] = bfhi(v0.x); f[2] = bflo(v0.y); f[3] = bfhi(v0.y); f[4] = bflo(v0.z); f[5] = bfhi(v0.z); f[6] = bflo(v0.w); f[7] = bfhi(v0.w);
;                 f[8] = bflo(v1.x); f[9] = bfhi(v1.x); f[10] = bflo(v1.y); f[11] = bfhi(v1.y); f[12] = bflo(v1.z); f[13] = bfhi(v1.z); f[14] = bflo(v1.w); f[15] = bfhi(v1.w);
;                 f[16] = bflo(v2.x); f[17] = bfhi(v2.x); f[18] = bflo(v2.y); f[19] = bfhi(v2.y); f[20] = bflo(v2.z); f[21] = bfhi(v2.z); f[22] = bflo(v2.w); f[23] = bfhi(v2.w);
;                 f[24] = bflo(v3.x); f[25] = bfhi(v3.x); f[26] = bflo(v3.y); f[27] = bfhi(v3.y); f[28] = bflo(v3.z); f[29] = bfhi(v3.z); f[30] = bflo(v3.w); f[31] = bfhi(v3.w);
;                 float ss = 0.f;
; #pragma unroll
;                 for (int e = 0; e < 32; ++e) ss += f[e] * f[e];
;                 ss += __shfl_xor(ss, 1); ss += __shfl_xor(ss, 2);
;                 const float r = 1.0f / sqrtf(ss * (1.f / 128.f) + EPS);
; #pragma unroll
;                 for (int e = 0; e < 32; e += 2) { const unsigned w = cvt_pk(f[e] * r, f[e + 1] * r);
;                     vT[(part * 32 + e) * 136 + j] = (bf16_t)(w & 0xffffu); vT[(part * 32 + e + 1) * 136 + j] = (bf16_t)(w >> 16); }
;             }
;             {
;                 const int gn = (g + 1) & 3, un = (g == 3) ? unit + G : unit;
;                 if (un < nunits) { const u32x4* src = (const u32x4*)(GV + (size_t)(un * 128 + j) * 512 + gn * 128 + part * 32); v0 = src[0]; v1 = src[1]; v2 = src[2]; v3 = src[3]; }
;             }
;             __syncthreads();
.LBB0_654:
	s_waitcnt vmcnt(0)
	v_and_b32_e32 v7, 0xffff0000, v44
	v_lshlrev_b32_e32 v6, 16, v44
	v_lshlrev_b32_e32 v26, 16, v38
	v_and_b32_e32 v27, 0xffff0000, v38
	v_mul_f32_e32 v38, v7, v7
	v_lshlrev_b32_e32 v8, 16, v45
	v_fmac_f32_e32 v38, v6, v6
	v_and_b32_e32 v9, 0xffff0000, v45
	v_fmac_f32_e32 v38, v8, v8
	v_lshlrev_b32_e32 v10, 16, v46
	v_fmac_f32_e32 v38, v9, v9
	v_and_b32_e32 v11, 0xffff0000, v46
	v_fmac_f32_e32 v38, v10, v10
	v_lshlrev_b32_e32 v12, 16, v47
	v_fmac_f32_e32 v38, v11, v11
	v_and_b32_e32 v13, 0xffff0000, v47
	v_fmac_f32_e32 v38, v12, v12
	v_lshlrev_b32_e32 v14, 16, v40
	v_fmac_f32_e32 v38, v13, v13
	v_and_b32_e32 v15, 0xffff0000, v40
	v_fmac_f32_e32 v38, v14, v14
	v_lshlrev_b32_e32 v16, 16, v41
	v_fmac_f32_e32 v38, v15, v15
	v_and_b32_e32 v17, 0xffff0000, v41
	v_fmac_f32_e32 v38, v16, v16
	v_lshlrev_b32_e32 v18, 16, v42
	v_fmac_f32_e32 v38, v17, v17
	v_and_b32_e32 v19, 0xffff0000, v42
	v_fmac_f32_e32 v38, v18, v18
	v_lshlrev_b32_e32 v20, 16, v43
	v_fmac_f32_e32 v38, v19, v19
	v_and_b32_e32 v21, 0xffff0000, v43
	v_fmac_f32_e32 v38, v20, v20
	v_lshlrev_b32_e32 v22, 16, v36
	v_fmac_f32_e32 v38, v21, v21
	v_and_b32_e32 v23, 0xffff0000, v36
	v_fmac_f32_e32 v38, v22, v22
	v_lshlrev_b32_e32 v24, 16, v37
	v_fmac_f32_e32 v38, v23, v23
	v_and_b32_e32 v25, 0xffff0000, v37
	v_fmac_f32_e32 v38, v24, v24
	v_fmac_f32_e32 v38, v25, v25
	v_fmac_f32_e32 v38, v26, v26
	v_lshlrev_b32_e32 v28, 16, v39
	v_fmac_f32_e32 v38, v27, v27
	v_and_b32_e32 v29, 0xffff0000, v39
	v_fmac_f32_e32 v38, v28, v28
	v_lshlrev_b32_e32 v30, 16, v32
	v_fmac_f32_e32 v38, v29, v29
	v_and_b32_e32 v31, 0xffff0000, v32
	v_fmac_f32_e32 v38, v30, v30
	v_lshlrev_b32_e32 v32, 16, v33
	v_fmac_f32_e32 v38, v31, v31
	v_and_b32_e32 v33, 0xffff0000, v33
	v_fmac_f32_e32 v38, v32, v32
	v_lshlrev_b32_e32 v36, 16, v34
	v_fmac_f32_e32 v38, v33, v33
	v_and_b32_e32 v34, 0xffff0000, v34
	v_fmac_f32_e32 v38, v36, v36
	v_lshlrev_b32_e32 v37, 16, v35
	v_fmac_f32_e32 v38, v34, v34
	v_and_b32_e32 v35, 0xffff0000, v35
	v_fmac_f32_e32 v38, v37, v37
	v_fmac_f32_e32 v38, v35, v35
	ds_bpermute_b32 v39, v167, v38
	v_ashrrev_i32_e32 v113, 31, v112
	v_lshlrev_b64 v[0:1], 8, v[112:113]
	v_lshl_add_u64 v[4:5], v[82:83], 0, v[0:1]
	global_load_dwordx4 v[0:3], v[4:5], off
	global_load_dwordx4 v[72:75], v[4:5], off offset:32
	global_load_dwordx4 v[68:71], v[4:5], off offset:64
	global_load_dwordx4 v[64:67], v[4:5], off offset:96
	global_load_dwordx4 v[60:63], v[4:5], off offset:128
	global_load_dwordx4 v[56:59], v[4:5], off offset:160
	global_load_dwordx4 v[52:55], v[4:5], off offset:192
	global_load_dwordx4 v[48:51], v[4:5], off offset:224
	s_waitcnt lgkmcnt(0)
	v_add_f32_e32 v38, v38, v39
	ds_bpermute_b32 v39, v168, v38
	v_lshl_add_u64 v[4:5], v[108:109], 0, s[34:35]
	s_brev_b32 s0, 48
	v_add_co_u32_e32 v4, vcc, s0, v4
	s_waitcnt lgkmcnt(0)
	v_add_f32_e32 v38, v38, v39
	v_addc_co_u32_e32 v5, vcc, 0, v5, vcc
	v_fmamk_f32 v38, v38, 0x3c000000, v79
	v_rsq_f32_e32 v39, v38
	s_nop 0
	global_load_dwordx2 v[130:131], v[4:5], off
	global_load_dwordx2 v[128:129], v[4:5], off offset:64
	global_load_dwordx2 v[126:127], v[4:5], off offset:16
	global_load_dwordx2 v[124:125], v[4:5], off offset:80
	global_load_dwordx2 v[122:123], v[4:5], off offset:32
	global_load_dwordx2 v[120:121], v[4:5], off offset:96
	global_load_dwordx2 v[118:119], v[4:5], off offset:48
	global_load_dwordx2 v[116:117], v[4:5], off offset:112
	v_lshl_add_u64 v[4:5], v[112:113], 2, s[60:61]
	global_load_dword v76, v[4:5], off
	s_mov_b64 s[0:1], 0x10000100
	v_mov_b32_e32 v4, v39
	v_mul_f32_e32 v5, v4, v6
	v_mul_f32_e32 v6, v4, v7
	v_cvt_pk_bf16_f32 v5, v5, v6
	ds_write_b16 v132, v5
	ds_write_b16_d16_hi v132, v5 offset:272
	v_mul_f32_e32 v5, v4, v8
	v_mul_f32_e32 v6, v4, v9
	v_cvt_pk_bf16_f32 v5, v5, v6
	ds_write_b16 v132, v5 offset:544
	ds_write_b16_d16_hi v132, v5 offset:816
	v_mul_f32_e32 v5, v4, v10
	v_mul_f32_e32 v6, v4, v11
	v_cvt_pk_bf16_f32 v5, v5, v6
	ds_write_b16 v132, v5 offset:1088
	ds_write_b16_d16_hi v132, v5 offset:1360
	v_mul_f32_e32 v5, v4, v12
	v_mul_f32_e32 v6, v4, v13
	v_cvt_pk_bf16_f32 v5, v5, v6
	ds_write_b16 v132, v5 offset:1632
	ds_write_b16_d16_hi v132, v5 offset:1904
	v_mul_f32_e32 v5, v4, v14
	v_mul_f32_e32 v6, v4, v15
	v_cvt_pk_bf16_f32 v5, v5, v6
	ds_write_b16 v132, v5 offset:2176
	ds_write_b16_d16_hi v132, v5 offset:2448
	v_mul_f32_e32 v5, v4, v16
	v_mul_f32_e32 v6, v4, v17
	v_cvt_pk_bf16_f32 v5, v5, v6
	ds_write_b16 v132, v5 offset:2720
	ds_write_b16_d16_hi v132, v5 offset:2992
	v_mul_f32_e32 v5, v4, v18
	v_mul_f32_e32 v6, v4, v19
	v_cvt_pk_bf16_f32 v5, v5, v6
	ds_write_b16 v132, v5 offset:3264
	ds_write_b16_d16_hi v132, v5 offset:3536
	v_mul_f32_e32 v5, v4, v20
	v_mul_f32_e32 v6, v4, v21
	v_cvt_pk_bf16_f32 v5, v5, v6
	ds_write_b16 v132, v5 offset:3808
	ds_write_b16_d16_hi v132, v5 offset:4080
	v_mul_f32_e32 v5, v4, v22
	v_mul_f32_e32 v6, v4, v23
	v_cvt_pk_bf16_f32 v5, v5, v6
	ds_write_b16 v132, v5 offset:4352
	ds_write_b16_d16_hi v132, v5 offset:4624
	v_mul_f32_e32 v5, v4, v24
	v_mul_f32_e32 v6, v4, v25
	v_cvt_pk_bf16_f32 v5, v5, v6
	ds_write_b16 v132, v5 offset:4896
	ds_write_b16_d16_hi v132, v5 offset:5168
	v_mul_f32_e32 v5, v4, v26
	v_mul_f32_e32 v6, v4, v27
	v_cvt_pk_bf16_f32 v5, v5, v6
	ds_write_b16 v132, v5 offset:5440
	ds_write_b16_d16_hi v132, v5 offset:5712
	v_mul_f32_e32 v5, v4, v28
	v_mul_f32_e32 v6, v4, v29
	v_cvt_pk_bf16_f32 v5, v5, v6
	ds_write_b16 v132, v5 offset:5984
	ds_write_b16_d16_hi v132, v5 offset:6256
	v_mul_f32_e32 v5, v4, v30
	v_mul_f32_e32 v6, v4, v31
	v_cvt_pk_bf16_f32 v5, v5, v6
	ds_write_b16 v132, v5 offset:6528
	ds_write_b16_d16_hi v132, v5 offset:6800
	v_mul_f32_e32 v5, v4, v32
	v_mul_f32_e32 v6, v4, v33
	v_cvt_pk_bf16_f32 v5, v5, v6
	ds_write_b16 v132, v5 offset:7072
	ds_write_b16_d16_hi v132, v5 offset:7344
	v_mul_f32_e32 v5, v4, v36
	v_mul_f32_e32 v6, v4, v34
	v_cvt_pk_bf16_f32 v5, v5, v6
	ds_write_b16 v132, v5 offset:7616
	ds_write_b16_d16_hi v132, v5 offset:7888
	v_mul_f32_e32 v5, v4, v37
	v_mul_f32_e32 v4, v4, v35
	v_cvt_pk_bf16_f32 v4, v5, v4
	ds_write_b16 v132, v4 offset:8160
	ds_write_b16_d16_hi v132, v4 offset:8432
	v_lshl_add_u64 v[4:5], v[106:107], 0, s[34:35]
	v_lshl_add_u64 v[6:7], v[4:5], 0, s[0:1]
	s_brev_b32 s0, 8
	v_add_co_u32_e32 v4, vcc, s0, v4
	s_brev_b32 s0, 20
	s_nop 0
	v_addc_co_u32_e32 v5, vcc, 0, v5, vcc
	global_load_dwordx4 v[44:47], v[4:5], off offset:256
	global_load_dwordx4 v[32:35], v[6:7], off offset:48
	global_load_dwordx4 v[36:39], v[6:7], off offset:32
	global_load_dwordx4 v[40:43], v[6:7], off offset:16
	s_waitcnt lgkmcnt(0)
	s_barrier
; #define LAS __attribute__((address_space(3)))
; __device__ __forceinline__ unsigned cvt_pk(float lo, float hi) { unsigned r; asm volatile("v_cvt_pk_bf16_f32 %0, %1, %2" : "=v"(r) : "v"(lo), "v"(hi)); return r; }
; __device__ __forceinline__ void gmlp_phase(const Params& p, LAS unsigned char* lds, int G) {
;     ...
;             f32x16 acc0, acc1;
; #pragma unroll
;             for (int e = 0; e < 16; ++e) { acc0[e] = 0.f; acc1[e] = 0.f; }
;             const LAS bf16_t* bp0 = vT + (64 * wc + l32) * 136 + 8 * hi; const LAS bf16_t* bp1 = bp0 + 32 * 136;
; #pragma unroll
;             for (int ks = 0; ks < 8; ++ks) {
;                 const bf16x8 b0 = *(const LAS bf16x8*)(bp0 + 16 * ks), b1 = *(const LAS bf16x8*)(bp1 + 16 * ks);
;                 acc0 = __builtin_amdgcn_mfma_f32_32x32x16_bf16(b0, wf[ks], acc0, 0, 0, 0);
;                 acc1 = __builtin_amdgcn_mfma_f32_32x32x16_bf16(b1, wf[ks], acc1, 0, 0, 0);
;             }
;             float yss = 0.f;
; #pragma unroll
;             for (int q = 0; q < 4; ++q) {
; #pragma unroll
;                 for (int hb = 0; hb < 2; ++hb) {
;                     const int c = cb + 32 * hb + 8 * q;
;                     const u32x2 gu = guv[2 * q + hb]; const f32x4 gv = *(const f32x4*)(gvn + c);
;                     const float a0 = hb ? acc1[4 * q] : acc0[4 * q], a1 = hb ? acc1[4 * q + 1] : acc0[4 * q + 1], a2 = hb ? acc1[4 * q + 2] : acc0[4 * q + 2], a3 = hb ? acc1[4 * q + 3] : acc0[4 * q + 3];
;                     const float y0 = bflo(gu.x) * (gv.x * a0 + bi), y1 = bfhi(gu.x) * (gv.y * a1 + bi), y2 = bflo(gu.y) * (gv.z * a2 + bi), y3 = bfhi(gu.y) * (gv.w * a3 + bi);
;                     yss += (y0 * y0 + y1 * y1) + (y2 * y2 + y3 * y3);
;                     u32x2 o; o.x = cvt_pk(y0, y1); o.y = cvt_pk(y2, y3);
;                     *(u32x2*)(Y + tok * 1024 + c) = o;
	ds_read_b128 v[4:7], v134
	ds_read_b128 v[136:139], v134 offset:32
	s_waitcnt vmcnt(20) lgkmcnt(1)
	v_mfma_f32_32x32x16_bf16 v[16:31], v[4:7], v[0:3], 0
	ds_read_b128 v[4:7], v134 offset:8704
	s_waitcnt vmcnt(19) lgkmcnt(1)
	v_mfma_f32_32x32x16_bf16 v[16:31], v[136:139], v[72:75], v[16:31]
	ds_read_b128 v[136:139], v134 offset:8736
	s_waitcnt lgkmcnt(1)
	v_mfma_f32_32x32x16_bf16 v[0:15], v[4:7], v[0:3], 0
	s_waitcnt lgkmcnt(0)
	v_mfma_f32_32x32x16_bf16 v[0:15], v[136:139], v[72:75], v[0:15]
	ds_read_b128 v[72:75], v134 offset:64
	s_waitcnt vmcnt(18) lgkmcnt(0)
	v_mfma_f32_32x32x16_bf16 v[16:31], v[72:75], v[68:71], v[16:31]
	ds_read_b128 v[72:75], v134 offset:8768
	s_waitcnt lgkmcnt(0)
	v_mfma_f32_32x32x16_bf16 v[0:15], v[72:75], v[68:71], v[0:15]
	ds_read_b128 v[68:71], v134 offset:96
	global_load_dwordx4 v[72:75], v[114:115], off offset:-224
	global_load_dwordx4 v[192:195], v[114:115], off offset:-96
	global_load_dwordx4 v[196:199], v[114:115], off offset:-192
	global_load_dwordx4 v[200:203], v[114:115], off offset:-64
	global_load_dwordx4 v[204:207], v[114:115], off offset:-160
	global_load_dwordx4 v[208:211], v[114:115], off offset:-32
	global_load_dwordx4 v[212:215], v[114:115], off offset:-128
	global_load_dwordx4 v[216:219], v[114:115], off
	s_waitcnt vmcnt(25) lgkmcnt(0)
	v_mfma_f32_32x32x16_bf16 v[16:31], v[68:71], v[64:67], v[16:31]
	ds_read_b128 v[68:71], v134 offset:8800
	s_waitcnt lgkmcnt(0)
	v_mfma_f32_32x32x16_bf16 v[0:15], v[68:71], v[64:67], v[0:15]
	ds_read_b128 v[64:67], v134 offset:128
	s_waitcnt vmcnt(24) lgkmcnt(0)
	v_mfma_f32_32x32x16_bf16 v[16:31], v[64:67], v[60:63], v[16:31]
	ds_read_b128 v[64:67], v134 offset:8832
	s_waitcnt lgkmcnt(0)
	v_mfma_f32_32x32x16_bf16 v[0:15], v[64:67], v[60:63], v[0:15]
	ds_read_b128 v[60:63], v134 offset:160
	s_waitcnt vmcnt(23) lgkmcnt(0)
	v_mfma_f32_32x32x16_bf16 v[16:31], v[60:63], v[56:59], v[16:31]
	ds_read_b128 v[60:63], v134 offset:8864
	s_waitcnt lgkmcnt(0)
	v_mfma_f32_32x32x16_bf16 v[0:15], v[60:63], v[56:59], v[0:15]
	ds_read_b128 v[56:59], v134 offset:192
	s_waitcnt vmcnt(22) lgkmcnt(0)
	v_mfma_f32_32x32x16_bf16 v[16:31], v[56:59], v[52:55], v[16:31]
	ds_read_b128 v[56:59], v134 offset:8896
	s_waitcnt lgkmcnt(0)
	v_mfma_f32_32x32x16_bf16 v[0:15], v[56:59], v[52:55], v[0:15]
	ds_read_b128 v[52:55], v134 offset:224
	ds_read_b128 v[56:59], v134 offset:8928
	s_waitcnt vmcnt(21) lgkmcnt(1)
	v_mfma_f32_32x32x16_bf16 v[16:31], v[52:55], v[48:51], v[16:31]
	s_waitcnt vmcnt(20)
	v_lshlrev_b32_e32 v52, 16, v130
	s_waitcnt lgkmcnt(0)
	v_mfma_f32_32x32x16_bf16 v[0:15], v[56:59], v[48:51], v[0:15]
	s_waitcnt vmcnt(0)
	s_nop 6
	v_fma_f32 v16, v16, v72, v76
	v_mul_f32_e32 v60, v16, v52
	v_and_b32_e32 v16, 0xffff0000, v130
	v_fma_f32 v17, v17, v73, v76
	v_mul_f32_e32 v61, v17, v16
	v_lshlrev_b32_e32 v16, 16, v131
	v_fma_f32 v17, v18, v74, v76
	v_mul_f32_e32 v62, v17, v16
	v_and_b32_e32 v16, 0xffff0000, v131
	v_fma_f32 v17, v19, v75, v76
	v_mul_f32_e32 v63, v17, v16
	v_lshl_add_u64 v[16:17], v[110:111], 0, s[34:35]
	v_add_co_u32_e32 v16, vcc, s0, v16
	v_cvt_pk_bf16_f32 v18, v60, v61
	v_cvt_pk_bf16_f32 v19, v62, v63
	v_lshlrev_b32_e32 v50, 16, v126
	s_nop 0
	v_addc_co_u32_e32 v17, vcc, 0, v17, vcc
	ds_write_b64 v140, v[18:19] offset:0
	s_nop 1
	v_mov_b64_e32 v[52:53], v[192:193]
	v_mov_b64_e32 v[54:55], v[194:195]
	v_lshlrev_b32_e32 v18, 16, v128
	v_and_b32_e32 v51, 0xffff0000, v126
	v_fma_f32 v0, v0, v52, v76
	v_mul_f32_e32 v18, v0, v18
	v_and_b32_e32 v0, 0xffff0000, v128
	v_fma_f32 v1, v1, v53, v76
	v_mul_f32_e32 v19, v1, v0
	v_lshlrev_b32_e32 v0, 16, v129
	v_fma_f32 v1, v2, v54, v76
	v_mul_f32_e32 v48, v1, v0
	v_and_b32_e32 v0, 0xffff0000, v129
	v_fma_f32 v1, v3, v55, v76
	v_mul_f32_e32 v49, v1, v0
	v_cvt_pk_bf16_f32 v0, v18, v19
	v_cvt_pk_bf16_f32 v1, v48, v49
	ds_write_b64 v140, v[0:1] offset:64
	s_nop 1
	v_mov_b64_e32 v[0:1], v[196:197]
	v_mov_b64_e32 v[2:3], v[198:199]
	v_lshlrev_b32_e32 v52, 16, v127
	v_and_b32_e32 v53, 0xffff0000, v127
	v_mul_f32_e32 v19, v19, v19
	v_mul_f32_e32 v49, v49, v49
	v_mul_f32_e32 v54, v61, v61
	v_mul_f32_e32 v55, v63, v63
	v_fmac_f32_e32 v19, v18, v18
	v_fmac_f32_e32 v49, v48, v48
	v_fmac_f32_e32 v54, v60, v60
	v_fmac_f32_e32 v55, v62, v62
	v_add_f32_e32 v18, v19, v49
	v_add_f32_e32 v54, v54, v55
	v_add_f32_e32 v18, v54, v18
	v_fma_f32 v0, v20, v0, v76
	v_fma_f32 v1, v21, v1, v76
	v_fma_f32 v2, v22, v2, v76
	v_fma_f32 v3, v23, v3, v76
	v_mul_f32_e32 v20, v0, v50
	v_mul_f32_e32 v21, v1, v51
	v_mul_f32_e32 v22, v2, v52
	v_mul_f32_e32 v23, v3, v53
	v_cvt_pk_bf16_f32 v0, v20, v21
	v_cvt_pk_bf16_f32 v1, v22, v23
	ds_write_b64 v140, v[0:1] offset:16
	s_nop 1
	v_mov_b64_e32 v[0:1], v[200:201]
	v_mov_b64_e32 v[2:3], v[202:203]
	v_lshlrev_b32_e32 v50, 16, v124
	v_and_b32_e32 v51, 0xffff0000, v124
	v_lshlrev_b32_e32 v52, 16, v125
	v_and_b32_e32 v53, 0xffff0000, v125
	v_mul_f32_e32 v19, v21, v21
	v_mul_f32_e32 v21, v23, v23
	v_fmac_f32_e32 v19, v20, v20
	v_fmac_f32_e32 v21, v22, v22
	v_add_f32_e32 v19, v19, v21
	v_add_f32_e32 v18, v18, v19
	v_fma_f32 v0, v4, v0, v76
	v_fma_f32 v1, v5, v1, v76
	v_fma_f32 v2, v6, v2, v76
	v_fma_f32 v3, v7, v3, v76
	v_mul_f32_e32 v4, v0, v50
	v_mul_f32_e32 v5, v1, v51
	v_mul_f32_e32 v6, v2, v52
	v_mul_f32_e32 v7, v3, v53
	v_cvt_pk_bf16_f32 v0, v4, v5
	v_cvt_pk_bf16_f32 v1, v6, v7
	ds_write_b64 v140, v[0:1] offset:80
	s_nop 1
	v_mov_b64_e32 v[0:1], v[204:205]
	v_mov_b64_e32 v[2:3], v[206:207]
	v_lshlrev_b32_e32 v50, 16, v122
	v_and_b32_e32 v51, 0xffff0000, v122
	v_lshlrev_b32_e32 v52, 16, v123
	v_and_b32_e32 v53, 0xffff0000, v123
	v_mul_f32_e32 v5, v5, v5
	v_mul_f32_e32 v7, v7, v7
	v_fmac_f32_e32 v5, v4, v4
	v_fmac_f32_e32 v7, v6, v6
; __device__ __forceinline__ unsigned cvt_pk(float lo, float hi) { unsigned r; asm volatile("v_cvt_pk_bf16_f32 %0, %1, %2" : "=v"(r) : "v"(lo), "v"(hi)); return r; }
; __device__ __forceinline__ void gmlp_phase(const Params& p, LAS unsigned char* lds, int G) {
;     ...
;             for (int q = 0; q < 4; ++q) {
; #pragma unroll
;                 for (int hb = 0; hb < 2; ++hb) {
;                     const int c = cb + 32 * hb + 8 * q;
;                     const u32x2 gu = guv[2 * q + hb]; const f32x4 gv = *(const f32x4*)(gvn + c);
;                     const float a0 = hb ? acc1[4 * q] : acc0[4 * q], a1 = hb ? acc1[4 * q + 1] : acc0[4 * q + 1], a2 = hb ? acc1[4 * q + 2] : acc0[4 * q + 2], a3 = hb ? acc1[4 * q + 3] : acc0[4 * q + 3];
;                     const float y0 = bflo(gu.x) * (gv.x * a0 + bi), y1 = bfhi(gu.x) * (gv.y * a1 + bi), y2 = bflo(gu.y) * (gv.z * a2 + bi), y3 = bfhi(gu.y) * (gv.w * a3 + bi);
;                     yss += (y0 * y0 + y1 * y1) + (y2 * y2 + y3 * y3);
;                     u32x2 o; o.x = cvt_pk(y0, y1); o.y = cvt_pk(y2, y3);
;                     *(u32x2*)(Y + tok * 1024 + c) = o;
;                 }
;             }
;             yss += __shfl_xor(yss, 32);
;             if (hi == 0) unsafeAtomicAdd(SSA + tok, yss);
	v_add_f32_e32 v4, v5, v7
	v_add_f32_e32 v4, v18, v4
	v_fma_f32 v0, v24, v0, v76
	v_fma_f32 v1, v25, v1, v76
	v_fma_f32 v2, v26, v2, v76
	v_fma_f32 v3, v27, v3, v76
	v_mul_f32_e32 v24, v0, v50
	v_mul_f32_e32 v25, v1, v51
	v_mul_f32_e32 v26, v2, v52
	v_mul_f32_e32 v27, v3, v53
	v_cvt_pk_bf16_f32 v0, v24, v25
	v_cvt_pk_bf16_f32 v1, v26, v27
	ds_write_b64 v140, v[0:1] offset:32
	s_nop 1
	v_mov_b64_e32 v[0:1], v[208:209]
	v_mov_b64_e32 v[2:3], v[210:211]
	v_lshlrev_b32_e32 v50, 16, v120
	v_and_b32_e32 v51, 0xffff0000, v120
	v_lshlrev_b32_e32 v52, 16, v121
	v_and_b32_e32 v53, 0xffff0000, v121
	v_mul_f32_e32 v5, v25, v25
	v_mul_f32_e32 v6, v27, v27
	v_fmac_f32_e32 v5, v24, v24
	v_fmac_f32_e32 v6, v26, v26
	v_add_f32_e32 v5, v5, v6
	v_add_f32_e32 v4, v4, v5
	v_fma_f32 v0, v8, v0, v76
	v_fma_f32 v1, v9, v1, v76
	v_fma_f32 v2, v10, v2, v76
	v_fma_f32 v3, v11, v3, v76
	v_mul_f32_e32 v8, v0, v50
	v_mul_f32_e32 v9, v1, v51
	v_mul_f32_e32 v10, v2, v52
	v_mul_f32_e32 v11, v3, v53
	v_cvt_pk_bf16_f32 v0, v8, v9
	v_cvt_pk_bf16_f32 v1, v10, v11
	ds_write_b64 v140, v[0:1] offset:96
	s_nop 1
	v_mov_b64_e32 v[0:1], v[212:213]
	v_mov_b64_e32 v[2:3], v[214:215]
	v_lshlrev_b32_e32 v50, 16, v118
	v_and_b32_e32 v51, 0xffff0000, v118
	v_lshlrev_b32_e32 v52, 16, v119
	v_and_b32_e32 v53, 0xffff0000, v119
	v_mul_f32_e32 v5, v9, v9
	v_mul_f32_e32 v6, v11, v11
	v_fmac_f32_e32 v5, v8, v8
	v_fmac_f32_e32 v6, v10, v10
	v_add_f32_e32 v5, v5, v6
	v_add_f32_e32 v4, v4, v5
	v_fma_f32 v0, v28, v0, v76
	v_fma_f32 v1, v29, v1, v76
	v_fma_f32 v2, v30, v2, v76
	v_fma_f32 v3, v31, v3, v76
	v_mul_f32_e32 v28, v0, v50
	v_mul_f32_e32 v29, v1, v51
	v_mul_f32_e32 v30, v2, v52
	v_mul_f32_e32 v31, v3, v53
	v_cvt_pk_bf16_f32 v0, v28, v29
	v_cvt_pk_bf16_f32 v1, v30, v31
	ds_write_b64 v140, v[0:1] offset:48
	s_nop 1
	v_mov_b64_e32 v[0:1], v[216:217]
	v_mov_b64_e32 v[2:3], v[218:219]
	v_mul_f32_e32 v5, v29, v29
	v_mul_f32_e32 v6, v31, v31
	v_fmac_f32_e32 v5, v28, v28
	v_fmac_f32_e32 v6, v30, v30
	v_and_b32_e32 v51, 0xffff0000, v116
	v_and_b32_e32 v53, 0xffff0000, v117
	v_add_f32_e32 v5, v5, v6
	v_lshlrev_b32_e32 v50, 16, v116
	v_lshlrev_b32_e32 v52, 16, v117
	v_add_f32_e32 v4, v4, v5
	v_fma_f32 v0, v12, v0, v76
	v_fma_f32 v1, v13, v1, v76
	v_fma_f32 v2, v14, v2, v76
	v_fmac_f32_e32 v76, v15, v3
	v_mul_f32_e32 v5, v1, v51
	v_mul_f32_e32 v7, v76, v53
	v_mul_f32_e32 v3, v0, v50
	v_mul_f32_e32 v6, v2, v52
	v_mul_f32_e32 v0, v5, v5
	v_mul_f32_e32 v1, v7, v7
	v_fmac_f32_e32 v0, v3, v3
	v_fmac_f32_e32 v1, v6, v6
	v_add_f32_e32 v0, v0, v1
	v_add_f32_e32 v0, v4, v0
	ds_bpermute_b32 v1, v169, v0
	v_cvt_pk_bf16_f32 v2, v3, v5
	v_cvt_pk_bf16_f32 v3, v6, v7
	ds_write_b64 v140, v[2:3] offset:112
	s_waitcnt lgkmcnt(0)
	ds_read_b128 v[148:151], v141 offset:0
	ds_read_b128 v[152:155], v141 offset:1152
	ds_read_b128 v[156:159], v141 offset:2304
	ds_read_b128 v[160:163], v141 offset:3456
	v_lshl_add_u64 v[164:165], v[16:17], 0, v[180:181]
	v_lshl_add_u64 v[170:171], v[16:17], 0, v[182:183]
	v_lshl_add_u64 v[172:173], v[16:17], 0, v[184:185]
	v_lshl_add_u64 v[174:175], v[16:17], 0, v[186:187]
	s_waitcnt lgkmcnt(0)
	global_store_dwordx4 v[164:165], v[148:151], off
	global_store_dwordx4 v[170:171], v[152:155], off
	global_store_dwordx4 v[172:173], v[156:159], off
	global_store_dwordx4 v[174:175], v[160:163], off
	s_and_saveexec_b64 s[0:1], s[38:39]
	s_cbranch_execz .LBB0_653
	s_waitcnt lgkmcnt(0)
	v_add_f32_e32 v0, v0, v1
	global_atomic_add_f32 v[102:103], v0, off
	s_branch .LBB0_653
; __device__ __forceinline__ void gmlp_phase(const Params& p, LAS unsigned char* lds, int G) {
;     ...
;     for (int unit = blockIdx.x; unit < nunits; unit += G) {
;         const int row0 = unit * 128;
;         for (int g = 0; g < 4; ++g) {
;             const int i = 32 * wi + l32; const size_t tok = (size_t)(row0 + i);
;             const int cb = g * 128 + 64 * wc + 4 * hi;
;             const bf16_t* ap = WSM + (size_t)(g * 128 + i) * 128 + 8 * hi;
;             bf16x8 wf[8]; u32x2 guv[8];
; #pragma unroll
;             for (int ks = 0; ks < 8; ++ks) wf[ks] = *(const bf16x8*)(ap + 16 * ks);
; #pragma unroll
;             for (int q = 0; q < 4; ++q) { guv[2 * q] = *(const u32x2*)(GU + tok * 512 + cb + 8 * q); guv[2 * q + 1] = *(const u32x2*)(GU + tok * 512 + cb + 32 + 8 * q); }
;             const float bi = bs[g * 128 + i];
;             {
;                 float f[32];
;                 f[0] = bflo(v0.x); f[1] = bfhi(v0.x); f[2] = bflo(v0.y); f[3] = bfhi(v0.y); f[4] = bflo(v0.z); f[5] = bfhi(v0.z); f[6] = bflo(v0.w); f[7] = bfhi(v0.w);
;                 f[8] = bflo(v1.x); f[9] = bfhi(v1.x); f[10] = bflo(v1.y); f[11] = bfhi(v1.y); f[12] = bflo(v1.z); f[13] = bfhi(v1.z); f[14] = bflo(v1.w); f[15] = bfhi(v1.w);
;                 f[16] = bflo(v2.x); f[17] = bfhi(v2.x); f[18] = bflo(v2.y); f[19] = bfhi(v2.y); f[20] = bflo(v2.z); f[21] = bfhi(v2.z); f[22] = bflo(v2.w); f[23] = bfhi(v2.w);
;                 f[24] = bflo(v3.x); f[25] = bfhi(v3.x); f[26] = bflo(v3.y); f[27] = bfhi(v3.y); f[28] = bflo(v3.z); f[29] = bfhi(v3.z); f[30] = bflo(v3.w); f[31] = bfhi(v3.w);
;                 float ss = 0.f;
; #pragma unroll
;                 for (int e = 0; e < 32; ++e) ss += f[e] * f[e];
;                 ss += __shfl_xor(ss, 1); ss += __shfl_xor(ss, 2);
;                 const float r = 1.0f / sqrtf(ss * (1.f / 128.f) + EPS);
; #pragma unroll
;                 for (int e = 0; e < 32; e += 2) { const unsigned w = cvt_pk(f[e] * r, f[e + 1] * r);
;                     vT[(part * 32 + e) * 136 + j] = (bf16_t)(w & 0xffffu); vT[(part * 32 + e + 1) * 136 + j] = (bf16_t)(w >> 16); }
;             }
;             {
;                 const int gn = (g + 1) & 3, un = (g == 3) ? unit + G : unit;
;                 if (un < nunits) { const u32x4* src = (const u32x4*)(GV + (size_t)(un * 128 + j) * 512 + gn * 128 + part * 32); v0 = src[0]; v1 = src[1]; v2 = src[2]; v3 = src[3]; }
.LBB0_656:
	v_and_b32_e32 v7, 0xffff0000, v44
	v_lshlrev_b32_e32 v6, 16, v44
	v_mul_f32_e32 v48, v7, v7
	v_lshlrev_b32_e32 v8, 16, v45
	v_fmac_f32_e32 v48, v6, v6
	v_and_b32_e32 v9, 0xffff0000, v45
	v_fmac_f32_e32 v48, v8, v8
	v_lshlrev_b32_e32 v10, 16, v46
	v_fmac_f32_e32 v48, v9, v9
	v_and_b32_e32 v11, 0xffff0000, v46
	v_fmac_f32_e32 v48, v10, v10
	v_lshlrev_b32_e32 v12, 16, v47
	v_fmac_f32_e32 v48, v11, v11
	v_and_b32_e32 v13, 0xffff0000, v47
	v_fmac_f32_e32 v48, v12, v12
	v_lshlrev_b32_e32 v14, 16, v40
	v_fmac_f32_e32 v48, v13, v13
	v_and_b32_e32 v15, 0xffff0000, v40
	v_fmac_f32_e32 v48, v14, v14
	v_lshlrev_b32_e32 v16, 16, v41
	v_fmac_f32_e32 v48, v15, v15
	v_and_b32_e32 v17, 0xffff0000, v41
	v_fmac_f32_e32 v48, v16, v16
	v_lshlrev_b32_e32 v18, 16, v42
	v_fmac_f32_e32 v48, v17, v17
	v_and_b32_e32 v19, 0xffff0000, v42
	v_fmac_f32_e32 v48, v18, v18
	v_lshlrev_b32_e32 v20, 16, v43
	v_fmac_f32_e32 v48, v19, v19
	v_and_b32_e32 v21, 0xffff0000, v43
	v_fmac_f32_e32 v48, v20, v20
	v_lshlrev_b32_e32 v22, 16, v36
	v_fmac_f32_e32 v48, v21, v21
	v_and_b32_e32 v23, 0xffff0000, v36
	v_fmac_f32_e32 v48, v22, v22
	v_lshlrev_b32_e32 v24, 16, v37
	v_fmac_f32_e32 v48, v23, v23
	v_and_b32_e32 v25, 0xffff0000, v37
	v_fmac_f32_e32 v48, v24, v24
	v_lshlrev_b32_e32 v26, 16, v38
	v_fmac_f32_e32 v48, v25, v25
	v_and_b32_e32 v27, 0xffff0000, v38
	v_fmac_f32_e32 v48, v26, v26
	v_lshlrev_b32_e32 v28, 16, v39
	v_fmac_f32_e32 v48, v27, v27
	v_and_b32_e32 v29, 0xffff0000, v39
	v_fmac_f32_e32 v48, v28, v28
	v_lshlrev_b32_e32 v30, 16, v32
	v_fmac_f32_e32 v48, v29, v29
	v_and_b32_e32 v31, 0xffff0000, v32
	v_fmac_f32_e32 v48, v30, v30
	v_lshlrev_b32_e32 v101, 16, v33
	v_fmac_f32_e32 v48, v31, v31
	v_and_b32_e32 v122, 0xffff0000, v33
	v_fmac_f32_e32 v48, v101, v101
	v_lshlrev_b32_e32 v123, 16, v34
	v_fmac_f32_e32 v48, v122, v122
	v_and_b32_e32 v124, 0xffff0000, v34
	v_fmac_f32_e32 v48, v123, v123
	v_lshlrev_b32_e32 v125, 16, v35
	v_fmac_f32_e32 v48, v124, v124
	v_and_b32_e32 v126, 0xffff0000, v35
	v_fmac_f32_e32 v48, v125, v125
	v_fmac_f32_e32 v48, v126, v126
	ds_bpermute_b32 v49, v167, v48
	v_lshlrev_b64 v[0:1], 10, v[104:105]
	v_lshl_add_u64 v[4:5], s[64:65], 0, v[0:1]
	v_lshlrev_b32_e32 v76, 1, v80
	v_lshl_add_u64 v[4:5], v[4:5], 0, v[76:77]
	s_waitcnt lgkmcnt(0)
	v_add_f32_e32 v97, v48, v49
	ds_bpermute_b32 v106, v168, v97
	global_load_dwordx4 v[0:3], v[86:87], off
	global_load_dwordx4 v[60:63], v[86:87], off offset:32
	global_load_dwordx4 v[72:75], v[86:87], off offset:64
	global_load_dwordx4 v[68:71], v[86:87], off offset:96
	global_load_dwordx4 v[64:67], v[86:87], off offset:128
	global_load_dwordx4 v[56:59], v[86:87], off offset:160
	global_load_dwordx4 v[52:55], v[86:87], off offset:192
	global_load_dwordx4 v[48:51], v[86:87], off offset:224
	global_load_dwordx2 v[120:121], v[4:5], off offset:768
	global_load_dwordx2 v[116:117], v[4:5], off offset:784
	global_load_dwordx2 v[112:113], v[4:5], off offset:800
	global_load_dwordx2 v[108:109], v[4:5], off offset:816
	s_waitcnt lgkmcnt(0)
	v_add_f32_e32 v97, v97, v106
	v_fmamk_f32 v97, v97, 0x3c000000, v79
	v_rsq_f32_e32 v127, v97
	s_nop 0
	s_add_i32 s6, s6, s3
	s_cmpk_gt_i32 s6, 0x1ff
	global_load_dwordx2 v[118:119], v[4:5], off offset:832
	global_load_dwordx2 v[114:115], v[4:5], off offset:848
	global_load_dwordx2 v[110:111], v[4:5], off offset:864
	global_load_dwordx2 v[106:107], v[4:5], off offset:880
	global_load_dword v97, v[88:89], off offset:1536
	s_cselect_b64 s[0:1], -1, 0
	v_mov_b32_e32 v4, v127
	v_mul_f32_e32 v5, v4, v6
	v_mul_f32_e32 v6, v4, v7
	v_cvt_pk_bf16_f32 v5, v5, v6
	ds_write_b16 v132, v5
	ds_write_b16_d16_hi v132, v5 offset:272
	v_mul_f32_e32 v5, v4, v8
	v_mul_f32_e32 v6, v4, v9
	v_cvt_pk_bf16_f32 v5, v5, v6
	ds_write_b16 v132, v5 offset:544
	ds_write_b16_d16_hi v132, v5 offset:816
	v_mul_f32_e32 v5, v4, v10
	v_mul_f32_e32 v6, v4, v11
	v_cvt_pk_bf16_f32 v5, v5, v6
	ds_write_b16 v132, v5 offset:1088
	ds_write_b16_d16_hi v132, v5 offset:1360
	v_mul_f32_e32 v5, v4, v12
	v_mul_f32_e32 v6, v4, v13
	v_cvt_pk_bf16_f32 v5, v5, v6
	ds_write_b16 v132, v5 offset:1632
	ds_write_b16_d16_hi v132, v5 offset:1904
	v_mul_f32_e32 v5, v4, v14
	v_mul_f32_e32 v6, v4, v15
	v_cvt_pk_bf16_f32 v5, v5, v6
	ds_write_b16 v132, v5 offset:2176
	ds_write_b16_d16_hi v132, v5 offset:2448
	v_mul_f32_e32 v5, v4, v16
	v_mul_f32_e32 v6, v4, v17
	v_cvt_pk_bf16_f32 v5, v5, v6
	ds_write_b16 v132, v5 offset:2720
	ds_write_b16_d16_hi v132, v5 offset:2992
	v_mul_f32_e32 v5, v4, v18
	v_mul_f32_e32 v6, v4, v19
	v_cvt_pk_bf16_f32 v5, v5, v6
	ds_write_b16 v132, v5 offset:3264
	ds_write_b16_d16_hi v132, v5 offset:3536
	v_mul_f32_e32 v5, v4, v20
	v_mul_f32_e32 v6, v4, v21
	v_cvt_pk_bf16_f32 v5, v5, v6
	ds_write_b16 v132, v5 offset:3808
	ds_write_b16_d16_hi v132, v5 offset:4080
	v_mul_f32_e32 v5, v4, v22
	v_mul_f32_e32 v6, v4, v23
	v_cvt_pk_bf16_f32 v5, v5, v6
	ds_write_b16 v132, v5 offset:4352
	ds_write_b16_d16_hi v132, v5 offset:4624
	v_mul_f32_e32 v5, v4, v24
	v_mul_f32_e32 v6, v4, v25
	v_cvt_pk_bf16_f32 v5, v5, v6
	ds_write_b16 v132, v5 offset:4896
	ds_write_b16_d16_hi v132, v5 offset:5168
	v_mul_f32_e32 v5, v4, v26
	v_mul_f32_e32 v6, v4, v27
	v_cvt_pk_bf16_f32 v5, v5, v6
	ds_write_b16 v132, v5 offset:5440
	ds_write_b16_d16_hi v132, v5 offset:5712
	v_mul_f32_e32 v5, v4, v28
	v_mul_f32_e32 v6, v4, v29
	v_cvt_pk_bf16_f32 v5, v5, v6
	ds_write_b16 v132, v5 offset:5984
	ds_write_b16_d16_hi v132, v5 offset:6256
	v_mul_f32_e32 v5, v4, v30
	v_mul_f32_e32 v6, v4, v31
	v_cvt_pk_bf16_f32 v5, v5, v6
	ds_write_b16 v132, v5 offset:6528
	ds_write_b16_d16_hi v132, v5 offset:6800
	v_mul_f32_e32 v5, v4, v101
	v_mul_f32_e32 v6, v4, v122
	v_cvt_pk_bf16_f32 v5, v5, v6
	ds_write_b16 v132, v5 offset:7072
	ds_write_b16_d16_hi v132, v5 offset:7344
	v_mul_f32_e32 v5, v4, v123
	v_mul_f32_e32 v6, v4, v124
	v_cvt_pk_bf16_f32 v5, v5, v6
	ds_write_b16 v132, v5 offset:7616
	ds_write_b16_d16_hi v132, v5 offset:7888
	v_mul_f32_e32 v5, v4, v125
	v_mul_f32_e32 v4, v4, v126
	v_cvt_pk_bf16_f32 v4, v5, v4
	s_and_b64 vcc, exec, s[0:1]
	ds_write_b16 v132, v4 offset:8160
	ds_write_b16_d16_hi v132, v4 offset:8432
	s_cbranch_vccnz .LBB0_658
	v_lshl_add_u32 v4, s6, 7, v81
	v_ashrrev_i32_e32 v5, 31, v4
	v_lshlrev_b64 v[4:5], 10, v[4:5]
	v_lshl_add_u64 v[4:5], v[84:85], 0, v[4:5]
	global_load_dwordx4 v[32:35], v[4:5], off offset:48
	global_load_dwordx4 v[36:39], v[4:5], off offset:32
	global_load_dwordx4 v[40:43], v[4:5], off offset:16
	global_load_dwordx4 v[44:47], v[4:5], off
